# v45 plus attention QK^T K-fragment double-buffering and the FNet B-epilogue Gt[off2] read hoist
# baseline (speedup 1.0000x reference)
; DI void finishSM(f32x16& p0, f32x16& p1, float alpha, float& l_reg, bf16x8& pa0, bf16x8& pa1, bf16x8& pa2, bf16x8& pa3) {
; #pragma unroll
;   for (int r = 0; r < 16; ++r) p1[r] = __builtin_amdgcn_exp2f(p1[r]);
;   float ps = 0;
; #pragma unroll
;   for (int r = 0; r < 16; ++r) ps += p0[r];
; #pragma unroll
;   for (int r = 0; r < 16; ++r) ps += p1[r];
;   { auto rr = __builtin_amdgcn_permlane32_swap(__float_as_uint(ps), __float_as_uint(ps), false, false);
;     ps = __uint_as_float(rr[0]) + __uint_as_float(rr[1]); }
;   l_reg = l_reg * alpha + ps;
;     ...
;   PK4(p0, 0, pa0); PK4(p0, 8, pa1); PK4(p1, 0, pa2); PK4(p1, 8, pa3);
; DI void qkt(f32x16& p0, f32x16& p1, const bf16_t* Ks, const bf16x8* qr, int r32, int hi) {
;   p0 = f32x16{}; p1 = f32x16{};
; #pragma unroll
;   for (int d0 = 0; d0 < 8; ++d0) { int cb = (d0 * 16 + hi * 8) * 2;
;     bf16x8 b0 = *reinterpret_cast<const bf16x8*>((const char*)Ks + KSWZ(r32, cb));
;     bf16x8 b1 = *reinterpret_cast<const bf16x8*>((const char*)Ks + KSWZ(32 + r32, cb));
;     p0 = __builtin_amdgcn_mfma_f32_32x32x16_bf16(b0, qr[d0], p0, 0, 0, 0);
;     p1 = __builtin_amdgcn_mfma_f32_32x32x16_bf16(b1, qr[d0], p1, 0, 0, 0); }
; }
.LBB0_2001:
	ds_read_b128 v[64:67], v204 offset:49152
	ds_read_b128 v[68:71], v204 offset:57344
	ds_read_b128 v[220:223], v205 offset:49152
	ds_read_b128 v[224:227], v205 offset:57344
	v_add_f32_e32 v160, 0, v175
	v_add_f32_e32 v160, v219, v160
	s_waitcnt lgkmcnt(3)
	v_mfma_f32_32x32x16_bf16 v[80:95], v[64:67], v[124:127], 0
	v_add_f32_e32 v160, v161, v160
	v_add_f32_e32 v160, v218, v160
	v_add_f32_e32 v160, v162, v160
	v_add_f32_e32 v160, v174, v160
	v_add_f32_e32 v160, v163, v160
	v_add_f32_e32 v160, v173, v160
	v_add_f32_e32 v160, v170, v160
	s_waitcnt lgkmcnt(2)
	v_mfma_f32_32x32x16_bf16 v[64:79], v[68:71], v[124:127], 0
	v_add_f32_e32 v160, v172, v160
	v_add_f32_e32 v160, v169, v160
	v_add_f32_e32 v160, v171, v160
	v_exp_f32_e32 v156, v156
	v_add_f32_e32 v160, v166, v160
	v_exp_f32_e32 v157, v157
	v_add_f32_e32 v160, v168, v160
	ds_read_b128 v[248:251], v206 offset:49152
	ds_read_b128 v[252:255], v206 offset:57344
	s_waitcnt lgkmcnt(3)
	v_mfma_f32_32x32x16_bf16 v[80:95], v[220:223], v[116:119], v[80:95]
	v_exp_f32_e32 v152, v152
	v_add_f32_e32 v160, v165, v160
	v_exp_f32_e32 v153, v153
	v_add_f32_e32 v160, v167, v160
	v_exp_f32_e32 v148, v148
	v_add_f32_e32 v160, v156, v160
	v_exp_f32_e32 v149, v149
	s_waitcnt lgkmcnt(2)
	v_mfma_f32_32x32x16_bf16 v[64:79], v[224:227], v[116:119], v[64:79]
	v_add_f32_e32 v160, v157, v160
	v_exp_f32_e32 v146, v146
	v_add_f32_e32 v160, v152, v160
	v_exp_f32_e32 v147, v147
	v_add_f32_e32 v160, v153, v160
	v_exp_f32_e32 v144, v144
	ds_read_b128 v[220:223], v208 offset:49152
	ds_read_b128 v[224:227], v208 offset:57344
	s_waitcnt lgkmcnt(3)
	v_mfma_f32_32x32x16_bf16 v[80:95], v[248:251], v[112:115], v[80:95]
	v_add_f32_e32 v160, v148, v160
	v_exp_f32_e32 v145, v145
	v_add_f32_e32 v160, v149, v160
	v_exp_f32_e32 v158, v158
	v_add_f32_e32 v160, v146, v160
	v_exp_f32_e32 v159, v159
	v_add_f32_e32 v160, v147, v160
	s_waitcnt lgkmcnt(2)
	v_mfma_f32_32x32x16_bf16 v[64:79], v[252:255], v[112:115], v[64:79]
	v_exp_f32_e32 v154, v154
	v_add_f32_e32 v160, v144, v160
	v_exp_f32_e32 v155, v155
	v_add_f32_e32 v160, v145, v160
	v_exp_f32_e32 v150, v150
	v_add_f32_e32 v160, v158, v160
	ds_read_b128 v[248:251], v210 offset:49152
	ds_read_b128 v[252:255], v210 offset:57344
	s_waitcnt lgkmcnt(3)
	v_mfma_f32_32x32x16_bf16 v[80:95], v[220:223], v[108:111], v[80:95]
	v_exp_f32_e32 v151, v151
	v_add_f32_e32 v160, v159, v160
	v_add_f32_e32 v160, v154, v160
	v_add_f32_e32 v160, v155, v160
	v_add_f32_e32 v160, v150, v160
	v_add_f32_e32 v216, v151, v160
	v_mov_b32_e32 v217, v216
	s_waitcnt lgkmcnt(2)
	v_mfma_f32_32x32x16_bf16 v[64:79], v[224:227], v[108:111], v[64:79]
	v_permlane32_swap_b32_e32 v216, v217
	ds_read_b128 v[220:223], v212 offset:49152
	ds_read_b128 v[224:227], v212 offset:57344
	s_waitcnt lgkmcnt(3)
	v_mfma_f32_32x32x16_bf16 v[80:95], v[248:251], v[104:107], v[80:95]
	s_waitcnt lgkmcnt(2)
	v_mfma_f32_32x32x16_bf16 v[64:79], v[252:255], v[104:107], v[64:79]
	ds_read_b128 v[248:251], v213 offset:49152
	ds_read_b128 v[252:255], v213 offset:57344
	s_waitcnt lgkmcnt(3)
	v_mfma_f32_32x32x16_bf16 v[80:95], v[220:223], v[100:103], v[80:95]
	s_waitcnt lgkmcnt(2)
	v_mfma_f32_32x32x16_bf16 v[64:79], v[224:227], v[100:103], v[64:79]
	ds_read_b128 v[220:223], v214 offset:49152
	ds_read_b128 v[224:227], v214 offset:57344
	s_waitcnt lgkmcnt(3)
	v_mfma_f32_32x32x16_bf16 v[80:95], v[248:251], v[96:99], v[80:95]
	s_waitcnt lgkmcnt(2)
	v_mfma_f32_32x32x16_bf16 v[64:79], v[252:255], v[96:99], v[64:79]
	v_cvt_pk_bf16_f32 v160, v175, v219
	v_cvt_pk_bf16_f32 v161, v161, v218
	v_cvt_pk_bf16_f32 v162, v162, v174
	v_cvt_pk_bf16_f32 v163, v163, v173
	v_cvt_pk_bf16_f32 v170, v170, v172
	v_cvt_pk_bf16_f32 v171, v169, v171
	s_waitcnt lgkmcnt(1)
	v_mfma_f32_32x32x16_bf16 v[80:95], v[220:223], v[120:123], v[80:95]
	v_cvt_pk_bf16_f32 v172, v166, v168
	v_cvt_pk_bf16_f32 v173, v165, v167
	v_cvt_pk_bf16_f32 v166, v156, v157
	v_cvt_pk_bf16_f32 v167, v152, v153
	v_cvt_pk_bf16_f32 v168, v148, v149
	v_cvt_pk_bf16_f32 v169, v146, v147
	v_cvt_pk_bf16_f32 v218, v144, v145
	s_waitcnt lgkmcnt(0)
	v_mfma_f32_32x32x16_bf16 v[64:79], v[224:227], v[120:123], v[64:79]
	v_cvt_pk_bf16_f32 v219, v158, v159
	v_cvt_pk_bf16_f32 v220, v154, v155
	v_permlane32_swap_b32_e32 v160, v162
	v_cvt_pk_bf16_f32 v221, v150, v151
	v_permlane32_swap_b32_e32 v218, v220
	v_permlane32_swap_b32_e32 v161, v163
	v_permlane32_swap_b32_e32 v170, v172
	v_permlane32_swap_b32_e32 v171, v173
	v_permlane32_swap_b32_e32 v166, v168
	v_permlane32_swap_b32_e32 v167, v169
	v_permlane32_swap_b32_e32 v219, v221
	v_add_co_u32_e32 v144, vcc, s29, v184
	s_mov_b32 s4, 0xffff0000
	s_nop 0
	v_addc_co_u32_e32 v145, vcc, -1, v185, vcc
	v_add_co_u32_e32 v148, vcc, s4, v184
	s_nop 1
	v_addc_co_u32_e32 v149, vcc, -1, v185, vcc
	v_add_co_u32_e32 v152, vcc, s30, v184
	global_load_dwordx4 v[144:147], v[144:145], off
	s_nop 0
	global_load_dwordx4 v[148:151], v[148:149], off
	v_addc_co_u32_e32 v153, vcc, -1, v185, vcc
	v_add_co_u32_e32 v156, vcc, s31, v184
	s_nop 1
	v_addc_co_u32_e32 v157, vcc, -1, v185, vcc
	global_load_dwordx4 v[152:155], v[152:153], off
	s_nop 0
	global_load_dwordx4 v[156:159], v[156:157], off
	ds_read_b64_tr_b16 v[222:223], v199 offset:0
	ds_read_b64_tr_b16 v[224:225], v199 offset:0x800
	ds_read_b64_tr_b16 v[230:231], v199 offset:0x1000
	ds_read_b64_tr_b16 v[232:233], v199 offset:0x1800
	ds_read_b64_tr_b16 v[234:235], v199 offset:0x2000
	ds_read_b64_tr_b16 v[236:237], v199 offset:0x2800
	ds_read_b64_tr_b16 v[238:239], v199 offset:0x3000
	ds_read_b64_tr_b16 v[240:241], v199 offset:0x3800
	s_waitcnt lgkmcnt(0)
; #define SBAR() __builtin_amdgcn_sched_barrier(0)
; DI void partialSM(f32x16& p0, f32x16& p1, float& m_reg, float& mn, float& alpha) {
;   constexpr float C = SCALE * 1.4426950408889634f;
;   float pmax = p0[0];
; #pragma unroll
;   for (int r = 1; r < 16; ++r) pmax = fmaxf(pmax, p0[r]);
; #pragma unroll
;   for (int r = 0; r < 16; ++r) pmax = fmaxf(pmax, p1[r]);
;   { auto rr = __builtin_amdgcn_permlane32_swap(__float_as_uint(pmax), __float_as_uint(pmax), false, false);
;     pmax = fmaxf(__uint_as_float(rr[0]), __uint_as_float(rr[1])); }
;   if (__builtin_expect(__all(pmax - m_reg <= THR / SCALE), 1)) { mn = m_reg; alpha = 1.f; }
;   else { mn = fmaxf(m_reg, pmax); alpha = __builtin_amdgcn_exp2f((m_reg - mn) * C); m_reg = mn; }
; template <int D0> DI void pv_one(f32x16& od, int vb, bf16x8 pa0, bf16x8 pa1, bf16x8 pa2, bf16x8 pa3) {
;   const s16x4 l0 = tr_read<v_rd_off(D0, 0, 0)>(vb), h0 = tr_read<v_rd_off(D0, 0, 1)>(vb), l1 = tr_read<v_rd_off(D0, 1, 0)>(vb), h1 = tr_read<v_rd_off(D0, 1, 1)>(vb);
;   const s16x4 l2 = tr_read<v_rd_off(D0, 2, 0)>(vb), h2 = tr_read<v_rd_off(D0, 2, 1)>(vb), l3 = tr_read<v_rd_off(D0, 3, 0)>(vb), h3 = tr_read<v_rd_off(D0, 3, 1)>(vb);
;   asm volatile("s_waitcnt lgkmcnt(0)" ::: "memory"); SBAR();
;     ...
;   od = __builtin_amdgcn_mfma_f32_32x32x16_bf16(pa0, PK(l0, h0), od, 0, 0, 0);
;   od = __builtin_amdgcn_mfma_f32_32x32x16_bf16(pa1, PK(l1, h1), od, 0, 0, 0);
;   od = __builtin_amdgcn_mfma_f32_32x32x16_bf16(pa2, PK(l2, h2), od, 0, 0, 0);
;   od = __builtin_amdgcn_mfma_f32_32x32x16_bf16(pa3, PK(l3, h3), od, 0, 0, 0);
;     ...
; }
; DI void pv_d0(f32x16* o, int vb, bf16x8 pa0, bf16x8 pa1, bf16x8 pa2, bf16x8 pa3) {
;   pv_one<0>(o[0], vb, pa0, pa1, pa2, pa3); pv_one<1>(o[1], vb, pa0, pa1, pa2, pa3); pv_one<2>(o[2], vb, pa0, pa1, pa2, pa3); pv_one<3>(o[3], vb, pa0, pa1, pa2, pa3);
; }
	s_nop 0
	v_mfma_f32_32x32x16_bf16 v[0:15], v[160:163], v[222:225], v[0:15]
	ds_read_b64_tr_b16 v[222:223], v199 offset:0x200
	ds_read_b64_tr_b16 v[224:225], v199 offset:0xa00
	v_mfma_f32_32x32x16_bf16 v[0:15], v[170:173], v[230:233], v[0:15]
	ds_read_b64_tr_b16 v[230:231], v199 offset:0x1200
	ds_read_b64_tr_b16 v[232:233], v199 offset:0x1a00
	v_mfma_f32_32x32x16_bf16 v[0:15], v[166:169], v[234:237], v[0:15]
	ds_read_b64_tr_b16 v[234:235], v199 offset:0x2200
	ds_read_b64_tr_b16 v[236:237], v199 offset:0x2a00
	ds_read_b64_tr_b16 v[242:243], v199 offset:0x3200
	ds_read_b64_tr_b16 v[244:245], v199 offset:0x3a00
	s_waitcnt lgkmcnt(0)
	v_mfma_f32_32x32x16_bf16 v[0:15], v[218:221], v[238:241], v[0:15]
	v_mfma_f32_32x32x16_bf16 v[48:63], v[160:163], v[222:225], v[48:63]
	ds_read_b64_tr_b16 v[222:223], v199 offset:0x400
	ds_read_b64_tr_b16 v[224:225], v199 offset:0xc00
	v_mfma_f32_32x32x16_bf16 v[48:63], v[170:173], v[230:233], v[48:63]
	ds_read_b64_tr_b16 v[230:231], v199 offset:0x1400
	ds_read_b64_tr_b16 v[232:233], v199 offset:0x1c00
	v_mfma_f32_32x32x16_bf16 v[48:63], v[166:169], v[234:237], v[48:63]
	ds_read_b64_tr_b16 v[234:235], v199 offset:0x2400
	ds_read_b64_tr_b16 v[236:237], v199 offset:0x2c00
	ds_read_b64_tr_b16 v[238:239], v199 offset:0x3400
	ds_read_b64_tr_b16 v[240:241], v199 offset:0x3c00
	s_waitcnt lgkmcnt(0)
	v_mfma_f32_32x32x16_bf16 v[48:63], v[218:221], v[242:245], v[48:63]
	v_mfma_f32_32x32x16_bf16 v[32:47], v[160:163], v[222:225], v[32:47]
	ds_read_b64_tr_b16 v[222:223], v199 offset:0x600
	ds_read_b64_tr_b16 v[224:225], v199 offset:0xe00
	v_mfma_f32_32x32x16_bf16 v[32:47], v[170:173], v[230:233], v[32:47]
	ds_read_b64_tr_b16 v[230:231], v199 offset:0x1600
	ds_read_b64_tr_b16 v[232:233], v199 offset:0x1e00
	v_mfma_f32_32x32x16_bf16 v[32:47], v[166:169], v[234:237], v[32:47]
	ds_read_b64_tr_b16 v[234:235], v199 offset:0x2600
	ds_read_b64_tr_b16 v[236:237], v199 offset:0x2e00
	ds_read_b64_tr_b16 v[242:243], v199 offset:0x3600
	ds_read_b64_tr_b16 v[244:245], v199 offset:0x3e00
	s_waitcnt lgkmcnt(0)
	v_mfma_f32_32x32x16_bf16 v[32:47], v[218:221], v[238:241], v[32:47]
	v_mfma_f32_32x32x16_bf16 v[16:31], v[160:163], v[222:225], v[16:31]
	v_max_f32_e32 v165, v81, v81
	v_max_f32_e32 v174, v80, v80
	v_max_f32_e32 v165, v174, v165
	v_max3_f32 v165, v165, v82, v83
	v_max3_f32 v165, v165, v84, v85
	v_max3_f32 v160, v165, v86, v87
	v_max3_f32 v160, v160, v88, v89
	v_max3_f32 v160, v160, v90, v91
	v_mfma_f32_32x32x16_bf16 v[16:31], v[170:173], v[230:233], v[16:31]
	v_max3_f32 v160, v160, v92, v93
	v_max3_f32 v160, v160, v94, v95
	v_max3_f32 v160, v160, v64, v65
	v_max3_f32 v160, v160, v66, v67
	v_max3_f32 v160, v160, v68, v69
	v_max3_f32 v160, v160, v70, v71
	v_max3_f32 v160, v160, v72, v73
	v_max3_f32 v160, v160, v74, v75
	v_mfma_f32_32x32x16_bf16 v[16:31], v[166:169], v[234:237], v[16:31]
	v_max3_f32 v160, v160, v76, v77
	v_max3_f32 v160, v160, v78, v79
	v_mov_b32_e32 v161, v160
	s_nop 1
	v_permlane32_swap_b32_e32 v160, v161
	v_max_f32_e32 v161, v161, v161
	v_max_f32_e32 v160, v160, v160
	v_max_f32_e32 v160, v160, v161
	v_max_f32_e32 v162, v164, v164
	v_sub_f32_e32 v161, v160, v164
	v_max_f32_e32 v160, v162, v160
	v_mfma_f32_32x32x16_bf16 v[16:31], v[218:221], v[242:245], v[16:31]
	v_sub_f32_e32 v162, v164, v160
	v_mul_f32_e32 v162, 0x3e0293ee, v162
	v_exp_f32_e32 v162, v162
	v_cmp_ge_f32_e32 vcc, s28, v161
	s_cmp_eq_u64 vcc, exec
	s_cselect_b64 s[4:5], -1, 0
	s_barrier
	s_waitcnt vmcnt(4)
	v_cndmask_b32_e64 v220, v162, 1.0, s[4:5]
	v_cmp_gt_f32_e32 vcc, 1.0, v220
	s_waitcnt vmcnt(4)
	ds_write_b128 v200, v[136:139]
	ds_write_b128 v201, v[140:143]
	ds_write_b128 v202, v[128:131] offset:32768
	ds_write_b128 v203, v[132:135] offset:32768
	s_cbranch_vccz .LBB0_2005
	s_and_saveexec_b64 s[10:11], s[0:1]
	ds_write_b32 v207, v220 offset:128
	s_or_b64 exec, exec, s[10:11]
	s_waitcnt lgkmcnt(0)
	v_add_u32_e32 v161, v197, v176
	ds_read_b128 v[166:169], v161 offset:224
	ds_read_b128 v[170:173], v161 offset:192
	ds_read_b128 v[222:225], v161 offset:160
	ds_read_b128 v[230:233], v161 offset:128
	s_waitcnt lgkmcnt(3)
	v_pk_mul_f32 v[12:13], v[12:13], v[166:167]
	s_waitcnt lgkmcnt(2)
	v_pk_mul_f32 v[8:9], v[8:9], v[170:171]
	s_waitcnt lgkmcnt(1)
	v_pk_mul_f32 v[4:5], v[4:5], v[222:223]
	v_pk_mul_f32 v[14:15], v[14:15], v[168:169]
	v_pk_mul_f32 v[10:11], v[10:11], v[172:173]
	v_pk_mul_f32 v[6:7], v[6:7], v[224:225]
	s_waitcnt lgkmcnt(0)
	v_pk_mul_f32 v[2:3], v[2:3], v[232:233]
	v_pk_mul_f32 v[0:1], v[0:1], v[230:231]
	v_pk_mul_f32 v[60:61], v[60:61], v[166:167]
	v_pk_mul_f32 v[56:57], v[56:57], v[170:171]
	v_pk_mul_f32 v[52:53], v[52:53], v[222:223]
	v_pk_mul_f32 v[62:63], v[62:63], v[168:169]
	v_pk_mul_f32 v[58:59], v[58:59], v[172:173]
	v_pk_mul_f32 v[54:55], v[54:55], v[224:225]
	v_pk_mul_f32 v[50:51], v[50:51], v[232:233]
	v_pk_mul_f32 v[48:49], v[48:49], v[230:231]
	v_pk_mul_f32 v[44:45], v[44:45], v[166:167]
	v_pk_mul_f32 v[40:41], v[40:41], v[170:171]
	v_pk_mul_f32 v[36:37], v[36:37], v[222:223]
	v_pk_mul_f32 v[46:47], v[46:47], v[168:169]
	v_pk_mul_f32 v[42:43], v[42:43], v[172:173]
	v_pk_mul_f32 v[38:39], v[38:39], v[224:225]
	v_pk_mul_f32 v[34:35], v[34:35], v[232:233]
	v_pk_mul_f32 v[32:33], v[32:33], v[230:231]
	v_pk_mul_f32 v[28:29], v[28:29], v[166:167]
	v_pk_mul_f32 v[24:25], v[24:25], v[170:171]
	v_pk_mul_f32 v[20:21], v[20:21], v[222:223]
	v_pk_mul_f32 v[30:31], v[30:31], v[168:169]
	v_pk_mul_f32 v[26:27], v[26:27], v[172:173]
	v_pk_mul_f32 v[22:23], v[22:23], v[224:225]
	v_pk_mul_f32 v[18:19], v[18:19], v[232:233]
	v_pk_mul_f32 v[16:17], v[16:17], v[230:231]
; DI void partialSM(f32x16& p0, f32x16& p1, float& m_reg, float& mn, float& alpha) {
;     ...
;   float mnC = -mn * C;
; #pragma unroll
;   for (int r = 0; r < 16; ++r) p0[r] = fmaf(p0[r], C, mnC);
; #pragma unroll
;   for (int r = 0; r < 16; ++r) p1[r] = fmaf(p1[r], C, mnC);
; #pragma unroll
;   for (int r = 0; r < 16; ++r) p0[r] = __builtin_amdgcn_exp2f(p0[r]);
; }
; DI void finishSM(f32x16& p0, f32x16& p1, float alpha, float& l_reg, bf16x8& pa0, bf16x8& pa1, bf16x8& pa2, bf16x8& pa3) {
; #pragma unroll
;   for (int r = 0; r < 16; ++r) p1[r] = __builtin_amdgcn_exp2f(p1[r]);
;   float ps = 0;
; #pragma unroll
;   for (int r = 0; r < 16; ++r) ps += p0[r];
; #pragma unroll
;   for (int r = 0; r < 16; ++r) ps += p1[r];
;   { auto rr = __builtin_amdgcn_permlane32_swap(__float_as_uint(ps), __float_as_uint(ps), false, false);
;     ps = __uint_as_float(rr[0]) + __uint_as_float(rr[1]); }
;   l_reg = l_reg * alpha + ps;
;     ...
;   PK4(p0, 0, pa0); PK4(p0, 8, pa1); PK4(p1, 0, pa2); PK4(p1, 8, pa3);
;     ...
; }
; DI void qkt(f32x16& p0, f32x16& p1, const bf16_t* Ks, const bf16x8* qr, int r32, int hi) {
;   p0 = f32x16{}; p1 = f32x16{};
; #pragma unroll
;   for (int d0 = 0; d0 < 8; ++d0) { int cb = (d0 * 16 + hi * 8) * 2;
;     bf16x8 b0 = *reinterpret_cast<const bf16x8*>((const char*)Ks + KSWZ(r32, cb));
;     bf16x8 b1 = *reinterpret_cast<const bf16x8*>((const char*)Ks + KSWZ(32 + r32, cb));
;     p0 = __builtin_amdgcn_mfma_f32_32x32x16_bf16(b0, qr[d0], p0, 0, 0, 0);
;     p1 = __builtin_amdgcn_mfma_f32_32x32x16_bf16(b1, qr[d0], p1, 0, 0, 0); }
; }
.LBB0_2005:
	v_cndmask_b32_e64 v218, v160, v164, s[4:5]
	v_mul_f32_e32 v219, 0xbe0293ee, v218
	v_fmamk_f32 v80, v80, 0x3e0293ee, v219
	v_fmamk_f32 v81, v81, 0x3e0293ee, v219
	v_fmamk_f32 v82, v82, 0x3e0293ee, v219
	v_fmamk_f32 v83, v83, 0x3e0293ee, v219
	v_fmamk_f32 v84, v84, 0x3e0293ee, v219
	v_fmamk_f32 v85, v85, 0x3e0293ee, v219
	v_fmamk_f32 v86, v86, 0x3e0293ee, v219
	v_fmamk_f32 v87, v87, 0x3e0293ee, v219
	v_fmamk_f32 v88, v88, 0x3e0293ee, v219
	v_fmamk_f32 v89, v89, 0x3e0293ee, v219
	v_fmamk_f32 v90, v90, 0x3e0293ee, v219
	v_fmamk_f32 v91, v91, 0x3e0293ee, v219
	v_fmamk_f32 v92, v92, 0x3e0293ee, v219
	v_fmamk_f32 v93, v93, 0x3e0293ee, v219
	v_fmamk_f32 v94, v94, 0x3e0293ee, v219
	v_fmamk_f32 v95, v95, 0x3e0293ee, v219
	v_exp_f32_e32 v160, v80
	v_exp_f32_e32 v175, v81
	v_exp_f32_e32 v161, v82
	v_exp_f32_e32 v174, v83
	v_exp_f32_e32 v162, v84
	v_exp_f32_e32 v173, v85
	v_exp_f32_e32 v163, v86
	v_exp_f32_e32 v172, v87
	v_exp_f32_e32 v164, v88
	v_exp_f32_e32 v171, v89
	v_exp_f32_e32 v165, v90
	v_exp_f32_e32 v170, v91
	v_exp_f32_e32 v166, v92
	v_exp_f32_e32 v169, v93
	v_exp_f32_e32 v167, v94
	v_exp_f32_e32 v168, v95
	v_fmamk_f32 v222, v69, 0x3e0293ee, v219
	v_fmamk_f32 v221, v76, 0x3e0293ee, v219
	v_fmamk_f32 v230, v64, 0x3e0293ee, v219
	v_fmamk_f32 v231, v65, 0x3e0293ee, v219
	v_fmamk_f32 v232, v66, 0x3e0293ee, v219
	v_fmamk_f32 v233, v67, 0x3e0293ee, v219
	v_fmamk_f32 v234, v68, 0x3e0293ee, v219
	v_fmamk_f32 v223, v70, 0x3e0293ee, v219
	v_fmamk_f32 v224, v71, 0x3e0293ee, v219
	v_fmamk_f32 v225, v72, 0x3e0293ee, v219
	v_fmamk_f32 v226, v73, 0x3e0293ee, v219
	v_fmamk_f32 v227, v74, 0x3e0293ee, v219
	v_fmamk_f32 v229, v75, 0x3e0293ee, v219
	v_fmamk_f32 v235, v77, 0x3e0293ee, v219
	v_fmamk_f32 v236, v78, 0x3e0293ee, v219
	v_fmac_f32_e32 v219, 0x3e0293ee, v79
	s_waitcnt lgkmcnt(0)
	s_barrier
	ds_read_b128 v[64:67], v204 offset:32768
	ds_read_b128 v[68:71], v204 offset:40960
	ds_read_b128 v[238:241], v205 offset:32768
	ds_read_b128 v[242:245], v205 offset:40960
	v_exp_f32_e32 v230, v230
	v_exp_f32_e32 v231, v231
	s_waitcnt lgkmcnt(3)
	v_mfma_f32_32x32x16_bf16 v[80:95], v[64:67], v[124:127], 0
	v_exp_f32_e32 v232, v232
	v_exp_f32_e32 v233, v233
	v_exp_f32_e32 v234, v234
	v_exp_f32_e32 v237, v222
	v_exp_f32_e32 v223, v223
	v_exp_f32_e32 v224, v224
	v_exp_f32_e32 v225, v225
	s_waitcnt lgkmcnt(2)
	v_mfma_f32_32x32x16_bf16 v[64:79], v[68:71], v[124:127], 0
	v_exp_f32_e32 v226, v226
	v_exp_f32_e32 v227, v227
	v_exp_f32_e32 v229, v229
	v_exp_f32_e32 v235, v235
	v_exp_f32_e32 v236, v236
	v_exp_f32_e32 v219, v219
	ds_read_b128 v[248:251], v206 offset:32768
	ds_read_b128 v[252:255], v206 offset:40960
	s_waitcnt lgkmcnt(3)
	v_mfma_f32_32x32x16_bf16 v[80:95], v[238:241], v[116:119], v[80:95]
	s_waitcnt lgkmcnt(2)
	v_mfma_f32_32x32x16_bf16 v[64:79], v[242:245], v[116:119], v[64:79]
	ds_read_b128 v[238:241], v208 offset:32768
	ds_read_b128 v[242:245], v208 offset:40960
	s_waitcnt lgkmcnt(3)
	v_mfma_f32_32x32x16_bf16 v[80:95], v[248:251], v[112:115], v[80:95]
	s_waitcnt lgkmcnt(2)
	v_mfma_f32_32x32x16_bf16 v[64:79], v[252:255], v[112:115], v[64:79]
	ds_read_b128 v[248:251], v210 offset:32768
	ds_read_b128 v[252:255], v210 offset:40960
	s_waitcnt lgkmcnt(3)
	v_mfma_f32_32x32x16_bf16 v[80:95], v[238:241], v[108:111], v[80:95]
	s_waitcnt lgkmcnt(2)
	v_mfma_f32_32x32x16_bf16 v[64:79], v[242:245], v[108:111], v[64:79]
	ds_read_b128 v[238:241], v212 offset:32768
	ds_read_b128 v[242:245], v212 offset:40960
	s_waitcnt lgkmcnt(3)
	v_mfma_f32_32x32x16_bf16 v[80:95], v[248:251], v[104:107], v[80:95]
	s_waitcnt lgkmcnt(2)
	v_mfma_f32_32x32x16_bf16 v[64:79], v[252:255], v[104:107], v[64:79]
	ds_read_b128 v[248:251], v213 offset:32768
	ds_read_b128 v[252:255], v213 offset:40960
	s_waitcnt lgkmcnt(3)
	v_mfma_f32_32x32x16_bf16 v[80:95], v[238:241], v[100:103], v[80:95]
	s_waitcnt lgkmcnt(2)
	v_mfma_f32_32x32x16_bf16 v[64:79], v[242:245], v[100:103], v[64:79]
	ds_read_b128 v[238:241], v214 offset:32768
	ds_read_b128 v[242:245], v214 offset:40960
	s_waitcnt lgkmcnt(3)
	v_mfma_f32_32x32x16_bf16 v[80:95], v[248:251], v[96:99], v[80:95]
	s_waitcnt lgkmcnt(2)
	v_mfma_f32_32x32x16_bf16 v[64:79], v[252:255], v[96:99], v[64:79]
	s_waitcnt lgkmcnt(1)
	v_mfma_f32_32x32x16_bf16 v[80:95], v[238:241], v[120:123], v[80:95]
	v_exp_f32_e32 v238, v221
	v_add_f32_e32 v221, 0, v160
	v_add_f32_e32 v221, v175, v221
	v_add_f32_e32 v221, v161, v221
	v_add_f32_e32 v221, v174, v221
	v_add_f32_e32 v221, v162, v221
	v_add_f32_e32 v221, v173, v221
	v_add_f32_e32 v221, v163, v221
	v_add_f32_e32 v221, v172, v221
	v_add_f32_e32 v221, v164, v221
	v_add_f32_e32 v221, v171, v221
	v_add_f32_e32 v221, v165, v221
	v_add_f32_e32 v221, v170, v221
	v_add_f32_e32 v221, v166, v221
	v_add_f32_e32 v221, v169, v221
	v_add_f32_e32 v221, v167, v221
	v_add_f32_e32 v221, v168, v221
	v_add_f32_e32 v221, v230, v221
	v_add_f32_e32 v221, v231, v221
	v_add_f32_e32 v221, v232, v221
	v_add_f32_e32 v221, v233, v221
	v_add_f32_e32 v221, v234, v221
	v_add_f32_e32 v221, v237, v221
	v_add_f32_e32 v221, v223, v221
	v_add_f32_e32 v221, v224, v221
	v_add_f32_e32 v221, v225, v221
	v_add_f32_e32 v221, v226, v221
	s_waitcnt lgkmcnt(0)
	v_mfma_f32_32x32x16_bf16 v[64:79], v[242:245], v[120:123], v[64:79]
	v_add_f32_e32 v221, v227, v221
	v_add_f32_e32 v221, v229, v221
	v_add_f32_e32 v221, v238, v221
	v_add_f32_e32 v221, v235, v221
	v_add_f32_e32 v221, v236, v221
	v_add_f32_e32 v221, v219, v221
	v_mov_b32_e32 v222, v221
	v_cvt_pk_bf16_f32 v160, v160, v175
	v_cvt_pk_bf16_f32 v161, v161, v174
	v_cvt_pk_bf16_f32 v162, v162, v173
	v_cvt_pk_bf16_f32 v163, v163, v172
	v_cvt_pk_bf16_f32 v164, v164, v171
	v_cvt_pk_bf16_f32 v165, v165, v170
	v_cvt_pk_bf16_f32 v166, v166, v169
	v_cvt_pk_bf16_f32 v167, v167, v168
	v_cvt_pk_bf16_f32 v168, v230, v231
	v_cvt_pk_bf16_f32 v169, v232, v233
	v_cvt_pk_bf16_f32 v170, v234, v237
	v_cvt_pk_bf16_f32 v171, v223, v224
	v_cvt_pk_bf16_f32 v172, v225, v226
	v_cvt_pk_bf16_f32 v173, v227, v229
	v_cvt_pk_bf16_f32 v174, v238, v235
	v_cvt_pk_bf16_f32 v175, v236, v219
	s_nop 1
	v_permlane32_swap_b32_e32 v221, v222
	v_permlane32_swap_b32_e32 v160, v162
	v_permlane32_swap_b32_e32 v161, v163
	v_permlane32_swap_b32_e32 v164, v166
	v_permlane32_swap_b32_e32 v165, v167
	v_permlane32_swap_b32_e32 v168, v170
	v_permlane32_swap_b32_e32 v169, v171
	v_permlane32_swap_b32_e32 v172, v174
	v_permlane32_swap_b32_e32 v173, v175
	s_cmp_gt_u32 s34, 32
	s_cselect_b64 s[10:11], -1, 0
	s_and_b64 vcc, exec, s[10:11]
	s_cbranch_vccnz .Lattn_skip_ld
	v_add_co_u32_e32 v128, vcc, 0xffff8000, v184
	s_nop 1
	v_addc_co_u32_e32 v129, vcc, -1, v185, vcc
	v_add_co_u32_e32 v130, vcc, 0xfdbf8000, v184
	s_nop 1
	v_addc_co_u32_e32 v131, vcc, -1, v185, vcc
	v_add_co_u32_e32 v132, vcc, 0xfdc00000, v184
	global_load_dwordx4 v[136:139], v[128:129], off
	s_nop 0
	global_load_dwordx4 v[128:131], v[130:131], off
	v_addc_co_u32_e32 v133, vcc, -1, v185, vcc
	global_load_dwordx4 v[140:143], v[184:185], off
	s_nop 0
	global_load_dwordx4 v[132:135], v[132:133], off
